# sg_stats now prefetches the next row's loads into shadow registers during the current row's reduction; on top of the DPP-reduction version
# baseline (speedup 1.0000x reference)
; DI void unpack8(const u32x4 w, float (&f)[8]) { f[0] = bflo(w.x); f[1] = bfhi(w.x); f[2] = bflo(w.y); f[3] = bfhi(w.y); f[4] = bflo(w.z); f[5] = bfhi(w.z); f[6] = bflo(w.w); f[7] = bfhi(w.w); }
; DI void sg_stats(const bf16_t* Z, float* stats, int gw, int ngw, int lane) {
;     for (int m = gw; m < T_TOK; m += ngw) {
;         const u32x4* zr = (const u32x4*)(Z + (size_t)m * 4096 + 2048) + lane;
;         float f[4][8]; float s = 0.f;
; #pragma unroll
;         for (int j = 0; j < 4; ++j) { unpack8(zr[64 * j], f[j]);
.LBB0_1086:
	s_or_b64 exec, exec, s[4:5]
	s_mov_b64 s[8:9], s[0:1]
	s_waitcnt lgkmcnt(0)
	v_mov_b32_e32 v0, v220
	s_barrier
	s_nop 0
	v_readfirstlane_b32 s4, v0
	s_ashr_i32 s5, s4, 6
	v_readlane_b32 s4, v253, 2
	s_add_i32 s4, s5, s4
	s_cmpk_gt_i32 s4, 0x3fff
	s_cbranch_scc1 .LBB0_1091
	v_and_b32_e32 v1, 64, v221
	v_xor_b32_e32 v2, 1, v221
	v_add_u32_e32 v1, 64, v1
	v_cmp_lt_i32_e32 vcc, v2, v1
	s_load_dwordx2 s[8:9], s[8:9], 0xb0
	v_and_b32_e32 v0, 63, v0
	v_cndmask_b32_e32 v2, v221, v2, vcc
	v_lshlrev_b32_e32 v4, 2, v2
	v_xor_b32_e32 v2, 2, v221
	v_cmp_lt_i32_e32 vcc, v2, v1
	s_waitcnt lgkmcnt(0)
	s_add_u32 s16, s8, 0x800000
	s_addc_u32 s17, s9, 0
	v_cndmask_b32_e32 v2, v221, v2, vcc
	v_lshlrev_b32_e32 v5, 2, v2
	v_xor_b32_e32 v2, 4, v221
	v_cmp_lt_i32_e32 vcc, v2, v1
	s_lshl_b32 s10, s2, 4
	s_lshl_b32 s5, s5, 1
	v_cndmask_b32_e32 v2, v221, v2, vcc
	v_lshlrev_b32_e32 v6, 2, v2
	v_xor_b32_e32 v2, 8, v221
	v_cmp_lt_i32_e32 vcc, v2, v1
	s_add_i32 s10, s10, s5
	s_ashr_i32 s5, s4, 31
	v_cndmask_b32_e32 v2, v221, v2, vcc
	v_lshlrev_b32_e32 v7, 2, v2
	v_xor_b32_e32 v2, 16, v221
	v_cmp_lt_i32_e32 vcc, v2, v1
	s_lshl_b32 s18, s86, 4
	s_lshl_b64 s[12:13], s[4:5], 13
	v_cndmask_b32_e32 v2, v221, v2, vcc
	v_lshlrev_b32_e32 v8, 2, v2
	v_xor_b32_e32 v2, 32, v221
	v_cmp_lt_i32_e32 vcc, v2, v1
	s_add_u32 s8, s8, s12
	s_addc_u32 s9, s9, s13
	v_cndmask_b32_e32 v1, v221, v2, vcc
	v_lshlrev_b32_e32 v9, 2, v1
	v_cmp_eq_u32_e32 vcc, 0, v0
	v_lshlrev_b32_e32 v0, 4, v0
	v_mov_b32_e32 v1, 0
	v_lshl_add_u64 v[2:3], s[8:9], 0, v[0:1]
	s_mov_b64 s[8:9], 0xf601000
	s_ashr_i32 s85, s84, 31
	v_lshl_add_u64 v[2:3], v[2:3], 0, s[8:9]
	s_lshl_b64 s[12:13], s[84:85], 13
	v_mov_b32_e32 v0, 0x358637bd
	s_mov_b32 s5, 0x800000
	global_load_dwordx4 v[44:47], v[2:3], off
	global_load_dwordx4 v[48:51], v[2:3], off offset:1024
	global_load_dwordx4 v[52:55], v[2:3], off offset:2048
	global_load_dwordx4 v[56:59], v[2:3], off offset:3072
	s_branch .LBB0_1089

; DI void unpack8(const u32x4 w, float (&f)[8]) { f[0] = bflo(w.x); f[1] = bfhi(w.x); f[2] = bflo(w.y); f[3] = bfhi(w.y); f[4] = bflo(w.z); f[5] = bfhi(w.z); f[6] = bflo(w.w); f[7] = bfhi(w.w); }
; DI void sg_stats(const bf16_t* Z, float* stats, int gw, int ngw, int lane) {
;     for (int m = gw; m < T_TOK; m += ngw) {
;         const u32x4* zr = (const u32x4*)(Z + (size_t)m * 4096 + 2048) + lane;
;         float f[4][8]; float s = 0.f;
; #pragma unroll
;         for (int j = 0; j < 4; ++j) { unpack8(zr[64 * j], f[j]);
; #pragma unroll
;             for (int e = 0; e < 8; ++e) s += f[j][e]; }
;         const float mean = wave_sum(s) * (1.f / 2048.f); float q = 0.f;
; #pragma unroll
;         for (int j = 0; j < 4; ++j)
; #pragma unroll
;             for (int e = 0; e < 8; ++e) { const float dd = f[j][e] - mean; q += dd * dd; }
;         const float rstd = rsqrtf(wave_sum(q) * (1.f / 2048.f) + EPS);
;         if (lane == 0) { stats[2 * m] = mean; stats[2 * m + 1] = rstd; }
.LBB0_1089:
	s_waitcnt lgkmcnt(0)
	s_waitcnt vmcnt(0)
	v_mov_b32_e32 v10, v44
	v_mov_b32_e32 v11, v45
	v_mov_b32_e32 v12, v46
	v_mov_b32_e32 v13, v47
	v_mov_b32_e32 v14, v48
	v_mov_b32_e32 v15, v49
	v_mov_b32_e32 v16, v50
	v_mov_b32_e32 v17, v51
	v_mov_b32_e32 v18, v52
	v_mov_b32_e32 v19, v53
	v_mov_b32_e32 v20, v54
	v_mov_b32_e32 v21, v55
	v_mov_b32_e32 v22, v56
	v_mov_b32_e32 v23, v57
	v_mov_b32_e32 v24, v58
	v_mov_b32_e32 v25, v59
	v_lshl_add_u64 v[60:61], v[2:3], 0, s[12:13]
	global_load_dwordx4 v[44:47], v[60:61], off
	global_load_dwordx4 v[48:51], v[60:61], off offset:1024
	global_load_dwordx4 v[52:55], v[60:61], off offset:2048
	global_load_dwordx4 v[56:59], v[60:61], off offset:3072
	v_lshlrev_b32_e32 v26, 16, v10
	v_and_b32_e32 v27, 0xffff0000, v10
	v_add_f32_e32 v10, 0, v26
	v_lshlrev_b32_e32 v28, 16, v11
	v_add_f32_e32 v10, v10, v27
	v_and_b32_e32 v11, 0xffff0000, v11
	v_add_f32_e32 v10, v10, v28
	v_lshlrev_b32_e32 v29, 16, v12
	v_add_f32_e32 v10, v10, v11
	v_and_b32_e32 v12, 0xffff0000, v12
	v_add_f32_e32 v10, v10, v29
	v_lshlrev_b32_e32 v30, 16, v13
	v_add_f32_e32 v10, v10, v12
	v_and_b32_e32 v13, 0xffff0000, v13
	v_add_f32_e32 v10, v10, v30
	v_lshlrev_b32_e32 v31, 16, v14
	v_add_f32_e32 v10, v10, v13
	v_and_b32_e32 v14, 0xffff0000, v14
	v_add_f32_e32 v10, v10, v31
	v_lshlrev_b32_e32 v32, 16, v15
	v_add_f32_e32 v10, v10, v14
	v_and_b32_e32 v15, 0xffff0000, v15
	v_add_f32_e32 v10, v10, v32
	v_lshlrev_b32_e32 v33, 16, v16
	v_add_f32_e32 v10, v10, v15
	v_and_b32_e32 v16, 0xffff0000, v16
	v_add_f32_e32 v10, v10, v33
	v_lshlrev_b32_e32 v34, 16, v17
	v_add_f32_e32 v10, v10, v16
	v_and_b32_e32 v17, 0xffff0000, v17
	v_add_f32_e32 v10, v10, v34
	v_lshlrev_b32_e32 v35, 16, v18
	v_add_f32_e32 v10, v10, v17
	v_and_b32_e32 v18, 0xffff0000, v18
	v_add_f32_e32 v10, v10, v35
	v_lshlrev_b32_e32 v36, 16, v19
	v_add_f32_e32 v10, v10, v18
	v_and_b32_e32 v19, 0xffff0000, v19
	v_add_f32_e32 v10, v10, v36
	v_lshlrev_b32_e32 v37, 16, v20
	v_add_f32_e32 v10, v10, v19
	v_and_b32_e32 v20, 0xffff0000, v20
	v_add_f32_e32 v10, v10, v37
	v_lshlrev_b32_e32 v38, 16, v21
	v_add_f32_e32 v10, v10, v20
	v_and_b32_e32 v21, 0xffff0000, v21
	v_add_f32_e32 v10, v10, v38
	v_lshlrev_b32_e32 v39, 16, v22
	v_add_f32_e32 v10, v10, v21
	v_and_b32_e32 v22, 0xffff0000, v22
	v_add_f32_e32 v10, v10, v39
	v_lshlrev_b32_e32 v40, 16, v23
	v_add_f32_e32 v10, v10, v22
	v_and_b32_e32 v23, 0xffff0000, v23
	v_add_f32_e32 v10, v10, v40
	v_lshlrev_b32_e32 v41, 16, v24
	v_add_f32_e32 v10, v10, v23
	v_and_b32_e32 v24, 0xffff0000, v24
	v_add_f32_e32 v10, v10, v41
	v_lshlrev_b32_e32 v42, 16, v25
	v_add_f32_e32 v10, v10, v24
	v_and_b32_e32 v25, 0xffff0000, v25
	v_add_f32_e32 v10, v10, v42
	v_add_f32_e32 v10, v10, v25
	s_waitcnt lgkmcnt(0)
	s_nop 1
	v_add_f32_dpp v10, v10, v10 quad_perm:[1,0,3,2] row_mask:0xf bank_mask:0xf
	s_waitcnt lgkmcnt(0)
	s_nop 1
	v_add_f32_dpp v10, v10, v10 quad_perm:[2,3,0,1] row_mask:0xf bank_mask:0xf
	s_waitcnt lgkmcnt(0)
	s_nop 1
	v_add_f32_dpp v10, v10, v10 row_half_mirror row_mask:0xf bank_mask:0xf
	s_waitcnt lgkmcnt(0)
	s_nop 1
	v_add_f32_dpp v10, v10, v10 row_mirror row_mask:0xf bank_mask:0xf
	ds_bpermute_b32 v43, v8, v10
	s_waitcnt lgkmcnt(0)
	v_add_f32_e32 v10, v10, v43
	ds_bpermute_b32 v43, v9, v10
	s_waitcnt lgkmcnt(0)
	v_add_f32_e32 v10, v10, v43
	v_fmac_f32_e32 v27, 0xba000000, v10
	v_fmac_f32_e32 v26, 0xba000000, v10
	v_mul_f32_e32 v27, v27, v27
	v_fmac_f32_e32 v28, 0xba000000, v10
	v_fmac_f32_e32 v27, v26, v26
	v_fmac_f32_e32 v11, 0xba000000, v10
	v_fmac_f32_e32 v27, v28, v28
	v_fmac_f32_e32 v29, 0xba000000, v10
	v_fmac_f32_e32 v27, v11, v11
	v_fmac_f32_e32 v12, 0xba000000, v10
	v_fmac_f32_e32 v27, v29, v29
	v_fmac_f32_e32 v30, 0xba000000, v10
	v_fmac_f32_e32 v27, v12, v12
	v_fmac_f32_e32 v13, 0xba000000, v10
	v_fmac_f32_e32 v27, v30, v30
	v_fmac_f32_e32 v31, 0xba000000, v10
	v_fmac_f32_e32 v27, v13, v13
	v_fmac_f32_e32 v14, 0xba000000, v10
	v_fmac_f32_e32 v27, v31, v31
	v_fmac_f32_e32 v32, 0xba000000, v10
	v_fmac_f32_e32 v27, v14, v14
	v_fmac_f32_e32 v15, 0xba000000, v10
	v_fmac_f32_e32 v27, v32, v32
	v_fmac_f32_e32 v33, 0xba000000, v10
	v_fmac_f32_e32 v27, v15, v15
	v_fmac_f32_e32 v16, 0xba000000, v10
	v_fmac_f32_e32 v27, v33, v33
	v_fmac_f32_e32 v34, 0xba000000, v10
	v_fmac_f32_e32 v27, v16, v16
	v_fmac_f32_e32 v17, 0xba000000, v10
	v_fmac_f32_e32 v27, v34, v34
	v_fmac_f32_e32 v35, 0xba000000, v10
	v_fmac_f32_e32 v27, v17, v17
	v_fmac_f32_e32 v18, 0xba000000, v10
	v_fmac_f32_e32 v27, v35, v35
	v_fmac_f32_e32 v36, 0xba000000, v10
	v_fmac_f32_e32 v27, v18, v18
	v_fmac_f32_e32 v19, 0xba000000, v10
	v_fmac_f32_e32 v27, v36, v36
	v_fmac_f32_e32 v37, 0xba000000, v10
	v_fmac_f32_e32 v27, v19, v19
	v_fmac_f32_e32 v20, 0xba000000, v10
	v_fmac_f32_e32 v27, v37, v37
	v_fmac_f32_e32 v38, 0xba000000, v10
	v_fmac_f32_e32 v27, v20, v20
	v_fmac_f32_e32 v21, 0xba000000, v10
	v_fmac_f32_e32 v27, v38, v38
	v_fmac_f32_e32 v39, 0xba000000, v10
	v_fmac_f32_e32 v27, v21, v21
	v_fmac_f32_e32 v22, 0xba000000, v10
	v_fmac_f32_e32 v27, v39, v39
	v_fmac_f32_e32 v40, 0xba000000, v10
	v_fmac_f32_e32 v27, v22, v22
	v_fmac_f32_e32 v23, 0xba000000, v10
	v_fmac_f32_e32 v27, v40, v40
	v_fmac_f32_e32 v41, 0xba000000, v10
	v_fmac_f32_e32 v27, v23, v23
	v_fmac_f32_e32 v24, 0xba000000, v10
	v_fmac_f32_e32 v27, v41, v41
	v_fmac_f32_e32 v42, 0xba000000, v10
	v_fmac_f32_e32 v27, v24, v24
	v_fmac_f32_e32 v27, v42, v42
	v_fmac_f32_e32 v25, 0xba000000, v10
	v_fmac_f32_e32 v27, v25, v25
	s_waitcnt lgkmcnt(0)
	s_nop 1
	v_add_f32_dpp v11, v27, v27 quad_perm:[1,0,3,2] row_mask:0xf bank_mask:0xf
	s_waitcnt lgkmcnt(0)
	s_nop 1
	v_add_f32_dpp v11, v11, v11 quad_perm:[2,3,0,1] row_mask:0xf bank_mask:0xf
	s_waitcnt lgkmcnt(0)
	s_nop 1
	v_add_f32_dpp v11, v11, v11 row_half_mirror row_mask:0xf bank_mask:0xf
	s_waitcnt lgkmcnt(0)
	s_nop 1
	v_add_f32_dpp v11, v11, v11 row_mirror row_mask:0xf bank_mask:0xf
	ds_bpermute_b32 v12, v8, v11
	s_waitcnt lgkmcnt(0)
	v_add_f32_e32 v11, v11, v12
	ds_bpermute_b32 v12, v9, v11
	s_and_saveexec_b64 s[14:15], vcc
	s_cbranch_execz .LBB0_1088
	s_waitcnt lgkmcnt(0)
	v_add_f32_e32 v11, v11, v12
	v_fmamk_f32 v11, v11, 0x3a000000, v0
	v_mul_f32_e32 v12, 0x4b800000, v11
	v_cmp_gt_f32_e64 s[8:9], s5, v11
	s_ashr_i32 s11, s10, 31
	s_lshl_b64 s[20:21], s[10:11], 2
	v_cndmask_b32_e64 v11, v11, v12, s[8:9]
	v_rsq_f32_e32 v11, v11
	s_add_u32 s20, s16, s20
	v_mul_f32_e32 v10, 0x3a000000, v10
	s_addc_u32 s21, s17, s21
	v_mul_f32_e32 v12, 0x45800000, v11
	v_cndmask_b32_e64 v11, v11, v12, s[8:9]
	global_store_dwordx2 v1, v[10:11], s[20:21]
	s_branch .LBB0_1088
